# diff unit epilogue: 16 row reductions batched hop-by-hop (80 serial LDS round trips -> 5), batched rcp/rsq, cvt_pk packing
# speedup vs baseline: 1.0027x; 1.0027x over previous
.LBB0_789:
	s_or_b64 exec, exec, s[2:3]
	v_readlane_b32 s0, v254, 9
	s_waitcnt lgkmcnt(0)
	v_and_b32_e32 v124, 64, v230
	v_add_u32_e32 v190, 64, v124
	v_or_b32_e32 v64, s0, v241
	v_lshlrev_b32_e32 v64, 2, v64
	global_load_dword v131, v64, s[4:5]
	v_xor_b32_e32 v124, 1, v230
	v_cmp_lt_i32_e32 vcc, v124, v190
	v_lshlrev_b32_e32 v152, 1, v241
	s_movk_i32 s2, 0x100
	v_cndmask_b32_e32 v124, v230, v124, vcc
	v_lshlrev_b32_e32 v202, 2, v124
	v_xor_b32_e32 v124, 2, v230
	v_cmp_lt_i32_e32 vcc, v124, v190
	s_mov_b64 s[0:1], 0
	global_load_dword v130, v64, s[4:5] offset:128
	v_cndmask_b32_e32 v124, v230, v124, vcc
	v_lshlrev_b32_e32 v203, 2, v124
	v_xor_b32_e32 v124, 4, v230
	v_cmp_lt_i32_e32 vcc, v124, v190
	global_load_dword v129, v64, s[4:5] offset:256
	v_cndmask_b32_e32 v124, v230, v124, vcc
	global_load_dword v128, v64, s[4:5] offset:384
	v_lshlrev_b32_e32 v204, 2, v124
	v_xor_b32_e32 v124, 8, v230
	v_cmp_lt_i32_e32 vcc, v124, v190
	v_cndmask_b32_e32 v124, v230, v124, vcc
	global_load_dwordx4 v[132:135], v[144:145], off
	global_load_dwordx4 v[120:123], v[144:145], off offset:1024
	global_load_dwordx4 v[116:119], v[144:145], off offset:2048
	global_load_dwordx4 v[112:115], v[144:145], off offset:3072
	s_mov_b64 s[100:101], 0x2000
	v_lshl_add_u64 v[146:147], v[144:145], 0, s[100:101]
	s_mov_b64 s[100:101], 0x3000
	v_lshl_add_u64 v[148:149], v[144:145], 0, s[100:101]
	global_load_dwordx4 v[108:111], v[146:147], off offset:-4096
	global_load_dwordx4 v[104:107], v[146:147], off offset:-3072
	global_load_dwordx4 v[100:103], v[146:147], off offset:-2048
	global_load_dwordx4 v[96:99], v[146:147], off offset:-1024
	global_load_dwordx4 v[92:95], v[146:147], off
	global_load_dwordx4 v[88:91], v[146:147], off offset:1024
	global_load_dwordx4 v[84:87], v[146:147], off offset:2048
	global_load_dwordx4 v[80:83], v[146:147], off offset:3072
	global_load_dwordx4 v[76:79], v[148:149], off
	global_load_dwordx4 v[72:75], v[148:149], off offset:1024
	global_load_dwordx4 v[68:71], v[148:149], off offset:2048
	global_load_dwordx4 v[64:67], v[148:149], off offset:3072
	ds_read_b64 v[126:127], v240 offset:49152
	v_lshlrev_b32_e32 v205, 2, v124
	v_xor_b32_e32 v124, 16, v230
	v_cmp_lt_i32_e32 vcc, v124, v190
	s_waitcnt lgkmcnt(0)
	v_rcp_f32_e32 v126, v126
	v_cndmask_b32_e32 v124, v230, v124, vcc
	v_lshlrev_b32_e32 v206, 2, v124
	v_lshlrev_b32_e32 v124, 5, v243
	v_mul_f32_e32 v126, s20, v126
	v_ashrrev_i32_e32 v125, 31, v124
	v_lshl_add_u64 v[124:125], v[124:125], 0, s[8:9]
	v_lshl_or_b32 v124, v242, 2, v124
	s_and_b64 vcc, exec, s[6:7]
	ds_read_b64 v[208:209], v240 offset:49152
	ds_read_b64 v[210:211], v240 offset:49160
	ds_read_b64 v[212:213], v240 offset:49184
	ds_read_b64 v[214:215], v240 offset:49192
	ds_read_b64 v[216:217], v240 offset:49216
	ds_read_b64 v[218:219], v240 offset:49224
	ds_read_b64 v[220:221], v240 offset:49248
	ds_read_b64 v[222:223], v240 offset:49256
	s_waitcnt vmcnt(0)
	v_mul_f32_e32 v131, v239, v131
	v_mul_f32_e32 v130, v239, v130
	v_mul_f32_e32 v129, v239, v129
	v_mul_f32_e32 v128, v239, v128
	s_waitcnt lgkmcnt(0)
	v_rcp_f32_e32 v208, v208
	v_rcp_f32_e32 v209, v209
	v_rcp_f32_e32 v210, v210
	v_rcp_f32_e32 v211, v211
	v_rcp_f32_e32 v212, v212
	v_rcp_f32_e32 v213, v213
	v_rcp_f32_e32 v214, v214
	v_rcp_f32_e32 v215, v215
	v_rcp_f32_e32 v216, v216
	v_rcp_f32_e32 v217, v217
	v_rcp_f32_e32 v218, v218
	v_rcp_f32_e32 v219, v219
	v_rcp_f32_e32 v220, v220
	v_rcp_f32_e32 v221, v221
	v_rcp_f32_e32 v222, v222
	v_rcp_f32_e32 v223, v223
	s_nop 0
	v_mul_f32_e32 v208, s20, v208
	v_mul_f32_e32 v209, s20, v209
	v_mul_f32_e32 v210, s20, v210
	v_mul_f32_e32 v211, s20, v211
	v_mul_f32_e32 v212, s20, v212
	v_mul_f32_e32 v213, s20, v213
	v_mul_f32_e32 v214, s20, v214
	v_mul_f32_e32 v215, s20, v215
	v_mul_f32_e32 v216, s20, v216
	v_mul_f32_e32 v217, s20, v217
	v_mul_f32_e32 v218, s20, v218
	v_mul_f32_e32 v219, s20, v219
	v_mul_f32_e32 v220, s20, v220
	v_mul_f32_e32 v221, s20, v221
	v_mul_f32_e32 v222, s20, v222
	v_mul_f32_e32 v223, s20, v223
	v_fma_f32 v32, -v32, v208, v133
	v_fma_f32 v48, -v48, v208, v132
	v_fma_f32 v16, -v16, v208, v134
	v_fma_f32 v0, -v0, v208, v135
	v_fma_f32 v33, -v33, v209, v121
	v_fma_f32 v49, -v49, v209, v120
	v_fma_f32 v17, -v17, v209, v122
	v_fma_f32 v1, -v1, v209, v123
	v_fma_f32 v34, -v34, v210, v117
	v_fma_f32 v50, -v50, v210, v116
	v_fma_f32 v18, -v18, v210, v118
	v_fma_f32 v2, -v2, v210, v119
	v_fma_f32 v35, -v35, v211, v113
	v_fma_f32 v51, -v51, v211, v112
	v_fma_f32 v19, -v19, v211, v114
	v_fma_f32 v3, -v3, v211, v115
	v_fma_f32 v36, -v36, v212, v109
	v_fma_f32 v52, -v52, v212, v108
	v_fma_f32 v20, -v20, v212, v110
	v_fma_f32 v4, -v4, v212, v111
	v_fma_f32 v37, -v37, v213, v105
	v_fma_f32 v53, -v53, v213, v104
	v_fma_f32 v21, -v21, v213, v106
	v_fma_f32 v5, -v5, v213, v107
	v_fma_f32 v38, -v38, v214, v101
	v_fma_f32 v54, -v54, v214, v100
	v_fma_f32 v22, -v22, v214, v102
	v_fma_f32 v6, -v6, v214, v103
	v_fma_f32 v39, -v39, v215, v97
	v_fma_f32 v55, -v55, v215, v96
	v_fma_f32 v23, -v23, v215, v98
	v_fma_f32 v7, -v7, v215, v99
	v_fma_f32 v40, -v40, v216, v93
	v_fma_f32 v56, -v56, v216, v92
	v_fma_f32 v24, -v24, v216, v94
	v_fma_f32 v8, -v8, v216, v95
	v_fma_f32 v41, -v41, v217, v89
	v_fma_f32 v57, -v57, v217, v88
	v_fma_f32 v25, -v25, v217, v90
	v_fma_f32 v9, -v9, v217, v91
	v_fma_f32 v42, -v42, v218, v85
	v_fma_f32 v58, -v58, v218, v84
	v_fma_f32 v26, -v26, v218, v86
	v_fma_f32 v10, -v10, v218, v87
	v_fma_f32 v43, -v43, v219, v81
	v_fma_f32 v59, -v59, v219, v80
	v_fma_f32 v27, -v27, v219, v82
	v_fma_f32 v11, -v11, v219, v83
	v_fma_f32 v44, -v44, v220, v77
	v_fma_f32 v60, -v60, v220, v76
	v_fma_f32 v28, -v28, v220, v78
	v_fma_f32 v12, -v12, v220, v79
	v_fma_f32 v45, -v45, v221, v73
	v_fma_f32 v61, -v61, v221, v72
	v_fma_f32 v29, -v29, v221, v74
	v_fma_f32 v13, -v13, v221, v75
	v_fma_f32 v46, -v46, v222, v69
	v_fma_f32 v62, -v62, v222, v68
	v_fma_f32 v30, -v30, v222, v70
	v_fma_f32 v14, -v14, v222, v71
	v_fma_f32 v47, -v47, v223, v65
	v_fma_f32 v63, -v63, v223, v64
	v_fma_f32 v31, -v31, v223, v66
	v_fma_f32 v15, -v15, v223, v67
	v_mul_f32_e32 v154, v32, v32
	v_fmac_f32_e32 v154, v48, v48
	v_fmac_f32_e32 v154, v16, v16
	v_fmac_f32_e32 v154, v0, v0
	v_mul_f32_e32 v155, v33, v33
	v_fmac_f32_e32 v155, v49, v49
	v_fmac_f32_e32 v155, v17, v17
	v_fmac_f32_e32 v155, v1, v1
	v_mul_f32_e32 v156, v34, v34
	v_fmac_f32_e32 v156, v50, v50
	v_fmac_f32_e32 v156, v18, v18
	v_fmac_f32_e32 v156, v2, v2
	v_mul_f32_e32 v157, v35, v35
	v_fmac_f32_e32 v157, v51, v51
	v_fmac_f32_e32 v157, v19, v19
	v_fmac_f32_e32 v157, v3, v3
	v_mul_f32_e32 v158, v36, v36
	v_fmac_f32_e32 v158, v52, v52
	v_fmac_f32_e32 v158, v20, v20
	v_fmac_f32_e32 v158, v4, v4
	v_mul_f32_e32 v159, v37, v37
	v_fmac_f32_e32 v159, v53, v53
	v_fmac_f32_e32 v159, v21, v21
	v_fmac_f32_e32 v159, v5, v5
	v_mul_f32_e32 v160, v38, v38
	v_fmac_f32_e32 v160, v54, v54
	v_fmac_f32_e32 v160, v22, v22
	v_fmac_f32_e32 v160, v6, v6
	v_mul_f32_e32 v161, v39, v39
	v_fmac_f32_e32 v161, v55, v55
	v_fmac_f32_e32 v161, v23, v23
	v_fmac_f32_e32 v161, v7, v7
	v_mul_f32_e32 v196, v40, v40
	v_fmac_f32_e32 v196, v56, v56
	v_fmac_f32_e32 v196, v24, v24
	v_fmac_f32_e32 v196, v8, v8
	v_mul_f32_e32 v197, v41, v41
	v_fmac_f32_e32 v197, v57, v57
	v_fmac_f32_e32 v197, v25, v25
	v_fmac_f32_e32 v197, v9, v9
	v_mul_f32_e32 v198, v42, v42
	v_fmac_f32_e32 v198, v58, v58
	v_fmac_f32_e32 v198, v26, v26
	v_fmac_f32_e32 v198, v10, v10
	v_mul_f32_e32 v199, v43, v43
	v_fmac_f32_e32 v199, v59, v59
	v_fmac_f32_e32 v199, v27, v27
	v_fmac_f32_e32 v199, v11, v11
	v_mul_f32_e32 v162, v44, v44
	v_fmac_f32_e32 v162, v60, v60
	v_fmac_f32_e32 v162, v28, v28
	v_fmac_f32_e32 v162, v12, v12
	v_mul_f32_e32 v163, v45, v45
	v_fmac_f32_e32 v163, v61, v61
	v_fmac_f32_e32 v163, v29, v29
	v_fmac_f32_e32 v163, v13, v13
	v_mul_f32_e32 v164, v46, v46
	v_fmac_f32_e32 v164, v62, v62
	v_fmac_f32_e32 v164, v30, v30
	v_fmac_f32_e32 v164, v14, v14
	v_mul_f32_e32 v165, v47, v47
	v_fmac_f32_e32 v165, v63, v63
	v_fmac_f32_e32 v165, v31, v31
	v_fmac_f32_e32 v165, v15, v15
	ds_bpermute_b32 v224, v202, v154
	ds_bpermute_b32 v225, v202, v155
	ds_bpermute_b32 v226, v202, v156
	ds_bpermute_b32 v227, v202, v157
	ds_bpermute_b32 v186, v202, v158
	ds_bpermute_b32 v187, v202, v159
	ds_bpermute_b32 v188, v202, v160
	ds_bpermute_b32 v189, v202, v161
	s_waitcnt lgkmcnt(0)
	v_add_f32_e32 v154, v154, v224
	v_add_f32_e32 v155, v155, v225
	v_add_f32_e32 v156, v156, v226
	v_add_f32_e32 v157, v157, v227
	v_add_f32_e32 v158, v158, v186
	v_add_f32_e32 v159, v159, v187
	v_add_f32_e32 v160, v160, v188
	v_add_f32_e32 v161, v161, v189
	ds_bpermute_b32 v224, v202, v196
	ds_bpermute_b32 v225, v202, v197
	ds_bpermute_b32 v226, v202, v198
	ds_bpermute_b32 v227, v202, v199
	ds_bpermute_b32 v186, v202, v162
	ds_bpermute_b32 v187, v202, v163
	ds_bpermute_b32 v188, v202, v164
	ds_bpermute_b32 v189, v202, v165
	s_waitcnt lgkmcnt(0)
	v_add_f32_e32 v196, v196, v224
	v_add_f32_e32 v197, v197, v225
	v_add_f32_e32 v198, v198, v226
	v_add_f32_e32 v199, v199, v227
	v_add_f32_e32 v162, v162, v186
	v_add_f32_e32 v163, v163, v187
	v_add_f32_e32 v164, v164, v188
	v_add_f32_e32 v165, v165, v189
	ds_bpermute_b32 v224, v203, v154
	ds_bpermute_b32 v225, v203, v155
	ds_bpermute_b32 v226, v203, v156
	ds_bpermute_b32 v227, v203, v157
	ds_bpermute_b32 v186, v203, v158
	ds_bpermute_b32 v187, v203, v159
	ds_bpermute_b32 v188, v203, v160
	ds_bpermute_b32 v189, v203, v161
	s_waitcnt lgkmcnt(0)
	v_add_f32_e32 v154, v154, v224
	v_add_f32_e32 v155, v155, v225
	v_add_f32_e32 v156, v156, v226
	v_add_f32_e32 v157, v157, v227
	v_add_f32_e32 v158, v158, v186
	v_add_f32_e32 v159, v159, v187
	v_add_f32_e32 v160, v160, v188
	v_add_f32_e32 v161, v161, v189
	ds_bpermute_b32 v224, v203, v196
	ds_bpermute_b32 v225, v203, v197
	ds_bpermute_b32 v226, v203, v198
	ds_bpermute_b32 v227, v203, v199
	ds_bpermute_b32 v186, v203, v162
	ds_bpermute_b32 v187, v203, v163
	ds_bpermute_b32 v188, v203, v164
	ds_bpermute_b32 v189, v203, v165
	s_waitcnt lgkmcnt(0)
	v_add_f32_e32 v196, v196, v224
	v_add_f32_e32 v197, v197, v225
	v_add_f32_e32 v198, v198, v226
	v_add_f32_e32 v199, v199, v227
	v_add_f32_e32 v162, v162, v186
	v_add_f32_e32 v163, v163, v187
	v_add_f32_e32 v164, v164, v188
	v_add_f32_e32 v165, v165, v189
	ds_bpermute_b32 v224, v204, v154
	ds_bpermute_b32 v225, v204, v155
	ds_bpermute_b32 v226, v204, v156
	ds_bpermute_b32 v227, v204, v157
	ds_bpermute_b32 v186, v204, v158
	ds_bpermute_b32 v187, v204, v159
	ds_bpermute_b32 v188, v204, v160
	ds_bpermute_b32 v189, v204, v161
	s_waitcnt lgkmcnt(0)
	v_add_f32_e32 v154, v154, v224
	v_add_f32_e32 v155, v155, v225
	v_add_f32_e32 v156, v156, v226
	v_add_f32_e32 v157, v157, v227
	v_add_f32_e32 v158, v158, v186
	v_add_f32_e32 v159, v159, v187
	v_add_f32_e32 v160, v160, v188
	v_add_f32_e32 v161, v161, v189
	ds_bpermute_b32 v224, v204, v196
	ds_bpermute_b32 v225, v204, v197
	ds_bpermute_b32 v226, v204, v198
	ds_bpermute_b32 v227, v204, v199
	ds_bpermute_b32 v186, v204, v162
	ds_bpermute_b32 v187, v204, v163
	ds_bpermute_b32 v188, v204, v164
	ds_bpermute_b32 v189, v204, v165
	s_waitcnt lgkmcnt(0)
	v_add_f32_e32 v196, v196, v224
	v_add_f32_e32 v197, v197, v225
	v_add_f32_e32 v198, v198, v226
	v_add_f32_e32 v199, v199, v227
	v_add_f32_e32 v162, v162, v186
	v_add_f32_e32 v163, v163, v187
	v_add_f32_e32 v164, v164, v188
	v_add_f32_e32 v165, v165, v189
	ds_bpermute_b32 v224, v205, v154
	ds_bpermute_b32 v225, v205, v155
	ds_bpermute_b32 v226, v205, v156
	ds_bpermute_b32 v227, v205, v157
	ds_bpermute_b32 v186, v205, v158
	ds_bpermute_b32 v187, v205, v159
	ds_bpermute_b32 v188, v205, v160
	ds_bpermute_b32 v189, v205, v161
	s_waitcnt lgkmcnt(0)
	v_add_f32_e32 v154, v154, v224
	v_add_f32_e32 v155, v155, v225
	v_add_f32_e32 v156, v156, v226
	v_add_f32_e32 v157, v157, v227
	v_add_f32_e32 v158, v158, v186
	v_add_f32_e32 v159, v159, v187
	v_add_f32_e32 v160, v160, v188
	v_add_f32_e32 v161, v161, v189
	ds_bpermute_b32 v224, v205, v196
	ds_bpermute_b32 v225, v205, v197
	ds_bpermute_b32 v226, v205, v198
	ds_bpermute_b32 v227, v205, v199
	ds_bpermute_b32 v186, v205, v162
	ds_bpermute_b32 v187, v205, v163
	ds_bpermute_b32 v188, v205, v164
	ds_bpermute_b32 v189, v205, v165
	s_waitcnt lgkmcnt(0)
	v_add_f32_e32 v196, v196, v224
	v_add_f32_e32 v197, v197, v225
	v_add_f32_e32 v198, v198, v226
	v_add_f32_e32 v199, v199, v227
	v_add_f32_e32 v162, v162, v186
	v_add_f32_e32 v163, v163, v187
	v_add_f32_e32 v164, v164, v188
	v_add_f32_e32 v165, v165, v189
	ds_bpermute_b32 v224, v206, v154
	ds_bpermute_b32 v225, v206, v155
	ds_bpermute_b32 v226, v206, v156
	ds_bpermute_b32 v227, v206, v157
	ds_bpermute_b32 v186, v206, v158
	ds_bpermute_b32 v187, v206, v159
	ds_bpermute_b32 v188, v206, v160
	ds_bpermute_b32 v189, v206, v161
	s_waitcnt lgkmcnt(0)
	v_add_f32_e32 v154, v154, v224
	v_add_f32_e32 v155, v155, v225
	v_add_f32_e32 v156, v156, v226
	v_add_f32_e32 v157, v157, v227
	v_add_f32_e32 v158, v158, v186
	v_add_f32_e32 v159, v159, v187
	v_add_f32_e32 v160, v160, v188
	v_add_f32_e32 v161, v161, v189
	ds_bpermute_b32 v224, v206, v196
	ds_bpermute_b32 v225, v206, v197
	ds_bpermute_b32 v226, v206, v198
	ds_bpermute_b32 v227, v206, v199
	ds_bpermute_b32 v186, v206, v162
	ds_bpermute_b32 v187, v206, v163
	ds_bpermute_b32 v188, v206, v164
	ds_bpermute_b32 v189, v206, v165
	s_waitcnt lgkmcnt(0)
	v_add_f32_e32 v196, v196, v224
	v_add_f32_e32 v197, v197, v225
	v_add_f32_e32 v198, v198, v226
	v_add_f32_e32 v199, v199, v227
	v_add_f32_e32 v162, v162, v186
	v_add_f32_e32 v163, v163, v187
	v_add_f32_e32 v164, v164, v188
	v_add_f32_e32 v165, v165, v189
	v_fmamk_f32 v154, v154, 0x3c000000, v228
	v_fmamk_f32 v155, v155, 0x3c000000, v228
	v_fmamk_f32 v156, v156, 0x3c000000, v228
	v_fmamk_f32 v157, v157, 0x3c000000, v228
	v_fmamk_f32 v158, v158, 0x3c000000, v228
	v_fmamk_f32 v159, v159, 0x3c000000, v228
	v_fmamk_f32 v160, v160, 0x3c000000, v228
	v_fmamk_f32 v161, v161, 0x3c000000, v228
	v_fmamk_f32 v196, v196, 0x3c000000, v228
	v_fmamk_f32 v197, v197, 0x3c000000, v228
	v_fmamk_f32 v198, v198, 0x3c000000, v228
	v_fmamk_f32 v199, v199, 0x3c000000, v228
	v_fmamk_f32 v162, v162, 0x3c000000, v228
	v_fmamk_f32 v163, v163, 0x3c000000, v228
	v_fmamk_f32 v164, v164, 0x3c000000, v228
	v_fmamk_f32 v165, v165, 0x3c000000, v228
	v_rsq_f32_e32 v154, v154
	v_rsq_f32_e32 v155, v155
	v_rsq_f32_e32 v156, v156
	v_rsq_f32_e32 v157, v157
	v_rsq_f32_e32 v158, v158
	v_rsq_f32_e32 v159, v159
	v_rsq_f32_e32 v160, v160
	v_rsq_f32_e32 v161, v161
	v_rsq_f32_e32 v196, v196
	v_rsq_f32_e32 v197, v197
	v_rsq_f32_e32 v198, v198
	v_rsq_f32_e32 v199, v199
	v_rsq_f32_e32 v162, v162
	v_rsq_f32_e32 v163, v163
	v_rsq_f32_e32 v164, v164
	v_rsq_f32_e32 v165, v165
	v_lshlrev_b64 v[200:201], 11, v[124:125]
	v_lshl_add_u64 v[200:201], s[42:43], 0, v[200:201]
	v_lshl_add_u64 v[200:201], v[200:201], 0, v[152:153]
	v_mul_f32_e32 v48, v48, v154
	v_mul_f32_e32 v32, v32, v154
	v_mul_f32_e32 v16, v16, v154
	v_mul_f32_e32 v0, v0, v154
	v_mul_f32_e32 v48, v131, v48
	v_mul_f32_e32 v32, v130, v32
	v_mul_f32_e32 v16, v129, v16
	v_mul_f32_e32 v0, v128, v0
	v_cvt_pk_bf16_f32 v48, v48, v48
	v_cvt_pk_bf16_f32 v32, v32, v32
	v_cvt_pk_bf16_f32 v16, v16, v16
	v_cvt_pk_bf16_f32 v0, v0, v0
	global_store_short v[200:201], v48, off offset:512
	global_store_short v[200:201], v32, off offset:576
	global_store_short v[200:201], v16, off offset:640
	global_store_short v[200:201], v0, off offset:704
	s_mov_b64 s[100:101], 0x800
	v_lshl_add_u64 v[146:147], v[200:201], 0, s[100:101]
	v_mul_f32_e32 v49, v49, v155
	v_mul_f32_e32 v33, v33, v155
	v_mul_f32_e32 v17, v17, v155
	v_mul_f32_e32 v1, v1, v155
	v_mul_f32_e32 v49, v131, v49
	v_mul_f32_e32 v33, v130, v33
	v_mul_f32_e32 v17, v129, v17
	v_mul_f32_e32 v1, v128, v1
	v_cvt_pk_bf16_f32 v49, v49, v49
	v_cvt_pk_bf16_f32 v33, v33, v33
	v_cvt_pk_bf16_f32 v17, v17, v17
	v_cvt_pk_bf16_f32 v1, v1, v1
	global_store_short v[146:147], v49, off offset:512
	global_store_short v[146:147], v33, off offset:576
	global_store_short v[146:147], v17, off offset:640
	global_store_short v[146:147], v1, off offset:704
	s_mov_b64 s[100:101], 0x1000
	v_lshl_add_u64 v[146:147], v[200:201], 0, s[100:101]
	v_mul_f32_e32 v50, v50, v156
	v_mul_f32_e32 v34, v34, v156
	v_mul_f32_e32 v18, v18, v156
	v_mul_f32_e32 v2, v2, v156
	v_mul_f32_e32 v50, v131, v50
	v_mul_f32_e32 v34, v130, v34
	v_mul_f32_e32 v18, v129, v18
	v_mul_f32_e32 v2, v128, v2
	v_cvt_pk_bf16_f32 v50, v50, v50
	v_cvt_pk_bf16_f32 v34, v34, v34
	v_cvt_pk_bf16_f32 v18, v18, v18
	v_cvt_pk_bf16_f32 v2, v2, v2
	global_store_short v[146:147], v50, off offset:512
	global_store_short v[146:147], v34, off offset:576
	global_store_short v[146:147], v18, off offset:640
	global_store_short v[146:147], v2, off offset:704
	s_mov_b64 s[100:101], 0x1800
	v_lshl_add_u64 v[146:147], v[200:201], 0, s[100:101]
	v_mul_f32_e32 v51, v51, v157
	v_mul_f32_e32 v35, v35, v157
	v_mul_f32_e32 v19, v19, v157
	v_mul_f32_e32 v3, v3, v157
	v_mul_f32_e32 v51, v131, v51
	v_mul_f32_e32 v35, v130, v35
	v_mul_f32_e32 v19, v129, v19
	v_mul_f32_e32 v3, v128, v3
	v_cvt_pk_bf16_f32 v51, v51, v51
	v_cvt_pk_bf16_f32 v35, v35, v35
	v_cvt_pk_bf16_f32 v19, v19, v19
	v_cvt_pk_bf16_f32 v3, v3, v3
	global_store_short v[146:147], v51, off offset:512
	global_store_short v[146:147], v35, off offset:576
	global_store_short v[146:147], v19, off offset:640
	global_store_short v[146:147], v3, off offset:704
	s_mov_b64 s[100:101], 0x4000
	v_lshl_add_u64 v[146:147], v[200:201], 0, s[100:101]
	v_mul_f32_e32 v52, v52, v158
	v_mul_f32_e32 v36, v36, v158
	v_mul_f32_e32 v20, v20, v158
	v_mul_f32_e32 v4, v4, v158
	v_mul_f32_e32 v52, v131, v52
	v_mul_f32_e32 v36, v130, v36
	v_mul_f32_e32 v20, v129, v20
	v_mul_f32_e32 v4, v128, v4
	v_cvt_pk_bf16_f32 v52, v52, v52
	v_cvt_pk_bf16_f32 v36, v36, v36
	v_cvt_pk_bf16_f32 v20, v20, v20
	v_cvt_pk_bf16_f32 v4, v4, v4
	global_store_short v[146:147], v52, off offset:512
	global_store_short v[146:147], v36, off offset:576
	global_store_short v[146:147], v20, off offset:640
	global_store_short v[146:147], v4, off offset:704
	s_mov_b64 s[100:101], 0x4800
	v_lshl_add_u64 v[146:147], v[200:201], 0, s[100:101]
	v_mul_f32_e32 v53, v53, v159
	v_mul_f32_e32 v37, v37, v159
	v_mul_f32_e32 v21, v21, v159
	v_mul_f32_e32 v5, v5, v159
	v_mul_f32_e32 v53, v131, v53
	v_mul_f32_e32 v37, v130, v37
	v_mul_f32_e32 v21, v129, v21
	v_mul_f32_e32 v5, v128, v5
	v_cvt_pk_bf16_f32 v53, v53, v53
	v_cvt_pk_bf16_f32 v37, v37, v37
	v_cvt_pk_bf16_f32 v21, v21, v21
	v_cvt_pk_bf16_f32 v5, v5, v5
	global_store_short v[146:147], v53, off offset:512
	global_store_short v[146:147], v37, off offset:576
	global_store_short v[146:147], v21, off offset:640
	global_store_short v[146:147], v5, off offset:704
	s_mov_b64 s[100:101], 0x5000
	v_lshl_add_u64 v[146:147], v[200:201], 0, s[100:101]
	v_mul_f32_e32 v54, v54, v160
	v_mul_f32_e32 v38, v38, v160
	v_mul_f32_e32 v22, v22, v160
	v_mul_f32_e32 v6, v6, v160
	v_mul_f32_e32 v54, v131, v54
	v_mul_f32_e32 v38, v130, v38
	v_mul_f32_e32 v22, v129, v22
	v_mul_f32_e32 v6, v128, v6
	v_cvt_pk_bf16_f32 v54, v54, v54
	v_cvt_pk_bf16_f32 v38, v38, v38
	v_cvt_pk_bf16_f32 v22, v22, v22
	v_cvt_pk_bf16_f32 v6, v6, v6
	global_store_short v[146:147], v54, off offset:512
	global_store_short v[146:147], v38, off offset:576
	global_store_short v[146:147], v22, off offset:640
	global_store_short v[146:147], v6, off offset:704
	s_mov_b64 s[100:101], 0x5800
	v_lshl_add_u64 v[146:147], v[200:201], 0, s[100:101]
	v_mul_f32_e32 v55, v55, v161
	v_mul_f32_e32 v39, v39, v161
	v_mul_f32_e32 v23, v23, v161
	v_mul_f32_e32 v7, v7, v161
	v_mul_f32_e32 v55, v131, v55
	v_mul_f32_e32 v39, v130, v39
	v_mul_f32_e32 v23, v129, v23
	v_mul_f32_e32 v7, v128, v7
	v_cvt_pk_bf16_f32 v55, v55, v55
	v_cvt_pk_bf16_f32 v39, v39, v39
	v_cvt_pk_bf16_f32 v23, v23, v23
	v_cvt_pk_bf16_f32 v7, v7, v7
	global_store_short v[146:147], v55, off offset:512
	global_store_short v[146:147], v39, off offset:576
	global_store_short v[146:147], v23, off offset:640
	global_store_short v[146:147], v7, off offset:704
	s_mov_b64 s[100:101], 0x8000
	v_lshl_add_u64 v[146:147], v[200:201], 0, s[100:101]
	v_mul_f32_e32 v56, v56, v196
	v_mul_f32_e32 v40, v40, v196
	v_mul_f32_e32 v24, v24, v196
	v_mul_f32_e32 v8, v8, v196
	v_mul_f32_e32 v56, v131, v56
	v_mul_f32_e32 v40, v130, v40
	v_mul_f32_e32 v24, v129, v24
	v_mul_f32_e32 v8, v128, v8
	v_cvt_pk_bf16_f32 v56, v56, v56
	v_cvt_pk_bf16_f32 v40, v40, v40
	v_cvt_pk_bf16_f32 v24, v24, v24
	v_cvt_pk_bf16_f32 v8, v8, v8
	global_store_short v[146:147], v56, off offset:512
	global_store_short v[146:147], v40, off offset:576
	global_store_short v[146:147], v24, off offset:640
	global_store_short v[146:147], v8, off offset:704
	s_mov_b64 s[100:101], 0x8800
	v_lshl_add_u64 v[146:147], v[200:201], 0, s[100:101]
	v_mul_f32_e32 v57, v57, v197
	v_mul_f32_e32 v41, v41, v197
	v_mul_f32_e32 v25, v25, v197
	v_mul_f32_e32 v9, v9, v197
	v_mul_f32_e32 v57, v131, v57
	v_mul_f32_e32 v41, v130, v41
	v_mul_f32_e32 v25, v129, v25
	v_mul_f32_e32 v9, v128, v9
	v_cvt_pk_bf16_f32 v57, v57, v57
	v_cvt_pk_bf16_f32 v41, v41, v41
	v_cvt_pk_bf16_f32 v25, v25, v25
	v_cvt_pk_bf16_f32 v9, v9, v9
	global_store_short v[146:147], v57, off offset:512
	global_store_short v[146:147], v41, off offset:576
	global_store_short v[146:147], v25, off offset:640
	global_store_short v[146:147], v9, off offset:704
	s_mov_b64 s[100:101], 0x9000
	v_lshl_add_u64 v[146:147], v[200:201], 0, s[100:101]
	v_mul_f32_e32 v58, v58, v198
	v_mul_f32_e32 v42, v42, v198
	v_mul_f32_e32 v26, v26, v198
	v_mul_f32_e32 v10, v10, v198
	v_mul_f32_e32 v58, v131, v58
	v_mul_f32_e32 v42, v130, v42
	v_mul_f32_e32 v26, v129, v26
	v_mul_f32_e32 v10, v128, v10
	v_cvt_pk_bf16_f32 v58, v58, v58
	v_cvt_pk_bf16_f32 v42, v42, v42
	v_cvt_pk_bf16_f32 v26, v26, v26
	v_cvt_pk_bf16_f32 v10, v10, v10
	global_store_short v[146:147], v58, off offset:512
	global_store_short v[146:147], v42, off offset:576
	global_store_short v[146:147], v26, off offset:640
	global_store_short v[146:147], v10, off offset:704
	s_mov_b64 s[100:101], 0x9800
	v_lshl_add_u64 v[146:147], v[200:201], 0, s[100:101]
	v_mul_f32_e32 v59, v59, v199
	v_mul_f32_e32 v43, v43, v199
	v_mul_f32_e32 v27, v27, v199
	v_mul_f32_e32 v11, v11, v199
	v_mul_f32_e32 v59, v131, v59
	v_mul_f32_e32 v43, v130, v43
	v_mul_f32_e32 v27, v129, v27
	v_mul_f32_e32 v11, v128, v11
	v_cvt_pk_bf16_f32 v59, v59, v59
	v_cvt_pk_bf16_f32 v43, v43, v43
	v_cvt_pk_bf16_f32 v27, v27, v27
	v_cvt_pk_bf16_f32 v11, v11, v11
	global_store_short v[146:147], v59, off offset:512
	global_store_short v[146:147], v43, off offset:576
	global_store_short v[146:147], v27, off offset:640
	global_store_short v[146:147], v11, off offset:704
	s_mov_b64 s[100:101], 0xc000
	v_lshl_add_u64 v[146:147], v[200:201], 0, s[100:101]
	v_mul_f32_e32 v60, v60, v162
	v_mul_f32_e32 v44, v44, v162
	v_mul_f32_e32 v28, v28, v162
	v_mul_f32_e32 v12, v12, v162
	v_mul_f32_e32 v60, v131, v60
	v_mul_f32_e32 v44, v130, v44
	v_mul_f32_e32 v28, v129, v28
	v_mul_f32_e32 v12, v128, v12
	v_cvt_pk_bf16_f32 v60, v60, v60
	v_cvt_pk_bf16_f32 v44, v44, v44
	v_cvt_pk_bf16_f32 v28, v28, v28
	v_cvt_pk_bf16_f32 v12, v12, v12
	global_store_short v[146:147], v60, off offset:512
	global_store_short v[146:147], v44, off offset:576
	global_store_short v[146:147], v28, off offset:640
	global_store_short v[146:147], v12, off offset:704
	s_mov_b64 s[100:101], 0xc800
	v_lshl_add_u64 v[146:147], v[200:201], 0, s[100:101]
	v_mul_f32_e32 v61, v61, v163
	v_mul_f32_e32 v45, v45, v163
	v_mul_f32_e32 v29, v29, v163
	v_mul_f32_e32 v13, v13, v163
	v_mul_f32_e32 v61, v131, v61
	v_mul_f32_e32 v45, v130, v45
	v_mul_f32_e32 v29, v129, v29
	v_mul_f32_e32 v13, v128, v13
	v_cvt_pk_bf16_f32 v61, v61, v61
	v_cvt_pk_bf16_f32 v45, v45, v45
	v_cvt_pk_bf16_f32 v29, v29, v29
	v_cvt_pk_bf16_f32 v13, v13, v13
	global_store_short v[146:147], v61, off offset:512
	global_store_short v[146:147], v45, off offset:576
	global_store_short v[146:147], v29, off offset:640
	global_store_short v[146:147], v13, off offset:704
	s_mov_b64 s[100:101], 0xd000
	v_lshl_add_u64 v[146:147], v[200:201], 0, s[100:101]
	v_mul_f32_e32 v62, v62, v164
	v_mul_f32_e32 v46, v46, v164
	v_mul_f32_e32 v30, v30, v164
	v_mul_f32_e32 v14, v14, v164
	v_mul_f32_e32 v62, v131, v62
	v_mul_f32_e32 v46, v130, v46
	v_mul_f32_e32 v30, v129, v30
	v_mul_f32_e32 v14, v128, v14
	v_cvt_pk_bf16_f32 v62, v62, v62
	v_cvt_pk_bf16_f32 v46, v46, v46
	v_cvt_pk_bf16_f32 v30, v30, v30
	v_cvt_pk_bf16_f32 v14, v14, v14
	global_store_short v[146:147], v62, off offset:512
	global_store_short v[146:147], v46, off offset:576
	global_store_short v[146:147], v30, off offset:640
	global_store_short v[146:147], v14, off offset:704
	s_mov_b64 s[100:101], 0xd800
	v_lshl_add_u64 v[146:147], v[200:201], 0, s[100:101]
	v_mul_f32_e32 v63, v63, v165
	v_mul_f32_e32 v47, v47, v165
	v_mul_f32_e32 v31, v31, v165
	v_mul_f32_e32 v15, v15, v165
	v_mul_f32_e32 v63, v131, v63
	v_mul_f32_e32 v47, v130, v47
	v_mul_f32_e32 v31, v129, v31
	v_mul_f32_e32 v15, v128, v15
	v_cvt_pk_bf16_f32 v63, v63, v63
	v_cvt_pk_bf16_f32 v47, v47, v47
	v_cvt_pk_bf16_f32 v31, v31, v31
	v_cvt_pk_bf16_f32 v15, v15, v15
	global_store_short v[146:147], v63, off offset:512
	global_store_short v[146:147], v47, off offset:576
	global_store_short v[146:147], v31, off offset:640
	global_store_short v[146:147], v15, off offset:704
	s_and_b64 vcc, exec, s[6:7]
	s_waitcnt vmcnt(63) expcnt(7) lgkmcnt(15)
	s_barrier
	s_cbranch_vccnz .LBB0_869
